# zig-zag MFMA order + next-unit queue pop issued before the end-of-unit store drain + out-proj epilogue: both halves residual loads issued up front + GEMM loop heads 64B-aligned
# speedup vs baseline: 1.0178x; 1.0030x over previous
.LBB0_126:
	s_mov_b32 s42, s41
	s_add_i32 s41, s41, 1
	s_cmp_lt_u32 s42, 3
	s_cselect_b64 s[24:25], -1, 0
	s_lshl_b32 s4, s41, 3
	s_or_b32 s4, s4, s34
	s_or_b32 s9, s4, s30
	s_and_b64 s[4:5], s[24:25], exec
	s_mov_b32 s26, s22
	s_cselect_b32 s22, s10, s22
	s_mov_b32 s43, s8
	s_cselect_b32 s8, s9, s8
	s_ashr_i32 s23, s22, 31
	s_lshl_b64 s[4:5], s[22:23], 20
	s_mov_b64 s[0:1], s[14:15]
	s_add_u32 s14, s44, s4
	s_addc_u32 s15, s45, s5
	s_and_b64 s[4:5], s[24:25], exec
	s_cselect_b32 s23, s15, s1
	s_cselect_b32 s27, s14, s0
	s_ashr_i32 s9, s8, 31
	s_lshl_b64 s[4:5], s[8:9], 20
	s_mov_b64 s[2:3], s[12:13]
	s_add_u32 s12, s28, s4
	s_addc_u32 s13, s29, s5
	s_and_b64 s[4:5], s[24:25], exec
	s_cselect_b32 s9, s13, s3
	s_cselect_b32 s46, s12, s2
	s_add_u32 s0, s0, 0x80080
	s_addc_u32 s1, s1, 0
	s_add_u32 s47, s2, 0x100
	v_mov_b32_e32 v2, 0
	s_addc_u32 s48, s3, 0
	s_mov_b32 s49, -2
	s_waitcnt lgkmcnt(0)
	v_mov_b32_e32 v3, v2
	v_mov_b32_e32 v4, v2
	v_mov_b32_e32 v5, v2
	v_mov_b32_e32 v6, v2
	v_mov_b32_e32 v7, v2
	v_mov_b32_e32 v8, v2
	v_mov_b32_e32 v9, v2
	v_mov_b32_e32 v18, v2
	v_mov_b32_e32 v19, v2
	v_mov_b32_e32 v20, v2
	v_mov_b32_e32 v21, v2
	v_mov_b32_e32 v22, v2
	v_mov_b32_e32 v23, v2
	v_mov_b32_e32 v24, v2
	v_mov_b32_e32 v25, v2
	v_mov_b32_e32 v34, v2
	v_mov_b32_e32 v35, v2
	v_mov_b32_e32 v36, v2
	v_mov_b32_e32 v37, v2
	v_mov_b32_e32 v38, v2
	v_mov_b32_e32 v39, v2
	v_mov_b32_e32 v40, v2
	v_mov_b32_e32 v41, v2
	v_mov_b32_e32 v50, v2
	v_mov_b32_e32 v51, v2
	v_mov_b32_e32 v52, v2
	v_mov_b32_e32 v53, v2
	v_mov_b32_e32 v54, v2
	v_mov_b32_e32 v55, v2
	v_mov_b32_e32 v56, v2
	v_mov_b32_e32 v57, v2
	v_mov_b32_e32 v10, v2
	v_mov_b32_e32 v11, v2
	v_mov_b32_e32 v12, v2
	v_mov_b32_e32 v13, v2
	v_mov_b32_e32 v14, v2
	v_mov_b32_e32 v15, v2
	v_mov_b32_e32 v16, v2
	v_mov_b32_e32 v17, v2
	v_mov_b32_e32 v26, v2
	v_mov_b32_e32 v27, v2
	v_mov_b32_e32 v28, v2
	v_mov_b32_e32 v29, v2
	v_mov_b32_e32 v30, v2
	v_mov_b32_e32 v31, v2
	v_mov_b32_e32 v32, v2
	v_mov_b32_e32 v33, v2
	v_mov_b32_e32 v42, v2
	v_mov_b32_e32 v43, v2
	v_mov_b32_e32 v44, v2
	v_mov_b32_e32 v45, v2
	v_mov_b32_e32 v46, v2
	v_mov_b32_e32 v47, v2
	v_mov_b32_e32 v48, v2
	v_mov_b32_e32 v49, v2
	v_mov_b32_e32 v58, v2
	v_mov_b32_e32 v59, v2
	v_mov_b32_e32 v60, v2
	v_mov_b32_e32 v61, v2
	v_mov_b32_e32 v62, v2
	v_mov_b32_e32 v63, v2
	v_mov_b32_e32 v64, v2
	v_mov_b32_e32 v65, v2
	v_mov_b32_e32 v66, v2
	v_mov_b32_e32 v67, v2
	v_mov_b32_e32 v68, v2
	v_mov_b32_e32 v69, v2
	v_mov_b32_e32 v70, v2
	v_mov_b32_e32 v71, v2
	v_mov_b32_e32 v72, v2
	v_mov_b32_e32 v73, v2
	v_mov_b32_e32 v82, v2
	v_mov_b32_e32 v83, v2
	v_mov_b32_e32 v84, v2
	v_mov_b32_e32 v85, v2
	v_mov_b32_e32 v86, v2
	v_mov_b32_e32 v87, v2
	v_mov_b32_e32 v88, v2
	v_mov_b32_e32 v89, v2
	v_mov_b32_e32 v98, v2
	v_mov_b32_e32 v99, v2
	v_mov_b32_e32 v100, v2
	v_mov_b32_e32 v101, v2
	v_mov_b32_e32 v102, v2
	v_mov_b32_e32 v103, v2
	v_mov_b32_e32 v104, v2
	v_mov_b32_e32 v105, v2
	v_mov_b32_e32 v114, v2
	v_mov_b32_e32 v115, v2
	v_mov_b32_e32 v116, v2
	v_mov_b32_e32 v117, v2
	v_mov_b32_e32 v118, v2
	v_mov_b32_e32 v119, v2
	v_mov_b32_e32 v120, v2
	v_mov_b32_e32 v121, v2
	v_mov_b32_e32 v74, v2
	v_mov_b32_e32 v75, v2
	v_mov_b32_e32 v76, v2
	v_mov_b32_e32 v77, v2
	v_mov_b32_e32 v78, v2
	v_mov_b32_e32 v79, v2
	v_mov_b32_e32 v80, v2
	v_mov_b32_e32 v81, v2
	v_mov_b32_e32 v90, v2
	v_mov_b32_e32 v91, v2
	v_mov_b32_e32 v92, v2
	v_mov_b32_e32 v93, v2
	v_mov_b32_e32 v94, v2
	v_mov_b32_e32 v95, v2
	v_mov_b32_e32 v96, v2
	v_mov_b32_e32 v97, v2
	v_mov_b32_e32 v106, v2
	v_mov_b32_e32 v107, v2
	v_mov_b32_e32 v108, v2
	v_mov_b32_e32 v109, v2
	v_mov_b32_e32 v110, v2
	v_mov_b32_e32 v111, v2
	v_mov_b32_e32 v112, v2
	v_mov_b32_e32 v113, v2
	v_mov_b32_e32 v122, v2
	v_mov_b32_e32 v123, v2
	v_mov_b32_e32 v124, v2
	v_mov_b32_e32 v125, v2
	v_mov_b32_e32 v126, v2
	v_mov_b32_e32 v127, v2
	v_mov_b32_e32 v128, v2
	v_mov_b32_e32 v129, v2
	.p2alignl 6, 3212836864

.LBB0_244:
	s_or_b64 exec, exec, s[2:3]
	s_lshl_b32 s0, s78, 9
	s_mov_b32 s1, s63
	s_mov_b32 s2, s0
	v_writelane_b32 v255, s2, 45
	s_lshl_b64 s[0:1], s[0:1], 2
	s_add_u32 s86, s56, s0
	v_writelane_b32 v255, s3, 46
	s_addc_u32 s87, s57, s1
	v_readlane_b32 s2, v255, 14
	s_add_u32 s83, s2, s0
	v_readlane_b32 s0, v255, 15
	s_addc_u32 s82, s0, s1
	s_lshl_b32 s62, s78, 7
	v_readlane_b32 s0, v255, 26
	s_lshl_b64 s[84:85], s[62:63], 2
	v_readlane_b32 s6, v255, 32
	v_readlane_b32 s7, v255, 33
	s_add_u32 s88, s6, s84
	v_readlane_b32 s8, v255, 34
	s_addc_u32 s89, s7, s85
	v_readlane_b32 s1, v255, 27
	v_readlane_b32 s9, v255, 35
	s_add_u32 s90, s8, s84
	v_readlane_b32 s10, v255, 36
	s_addc_u32 s91, s9, s85
	s_mul_i32 s1, s78, 0x2800
	v_readlane_b32 s11, v255, 37
	s_mul_hi_u32 s0, s78, 0x2800
	s_add_u32 s92, s10, s1
	v_mov_b32_e32 v0, v243
	s_waitcnt lgkmcnt(0)
	s_barrier
	s_addc_u32 s93, s11, s0
	v_readlane_b32 s4, v255, 30
	v_and_b32_e32 v2, 63, v0
	v_readfirstlane_b32 s0, v0
	v_readlane_b32 s5, v255, 31
	s_cmp_lt_u32 s0, 64
	v_lshlrev_b32_e32 v0, 8, v2
	s_cselect_b64 s[94:95], -1, 0
	s_mov_b32 s52, 0
	s_mov_b32 s32, 0
	v_cmp_eq_u32_e64 s[10:11], 0, v2
	v_cmp_gt_u32_e64 s[4:5], 8, v2
	v_lshl_add_u64 v[180:181], s[86:87], 0, v[0:1]
	s_mov_b32 s55, s54
	s_mov_b32 s97, s54
	v_readlane_b32 s2, v255, 28
	v_readlane_b32 s3, v255, 29
	v_readlane_b32 s12, v255, 38
	v_readlane_b32 s13, v255, 39
	v_readlane_b32 s14, v255, 40
	v_readlane_b32 s15, v255, 41
	s_branch .LBB0_247

.LBB0_247:
	s_andn2_b64 vcc, exec, s[94:95]
	s_cbranch_vccnz .LBB0_261
	s_mov_b32 s67, s97
	s_mov_b64 s[96:97], s[66:67]
	s_cmp_eq_u32 s32, 0
	s_cbranch_scc1 .LBB0_251
	s_mov_b32 s32, 0
	v_mov_b32_e32 v0, v10
	s_branch .Lpop_have

.Lpop_have:
	s_waitcnt vmcnt(0)
	v_readfirstlane_b32 s2, v0
	s_cmp_lt_u32 s2, 64
	s_cbranch_scc1 .LBB0_249
	s_mov_b64 s[0:1], 0
	s_mov_b64 s[6:7], 0
	s_and_saveexec_b64 s[2:3], s[4:5]
	s_cbranch_execz .LBB0_256
	global_load_dword v0, v[180:181], off sc1
	s_waitcnt vmcnt(0)
	v_cmp_gt_u32_e32 vcc, 64, v0
	s_and_b64 s[6:7], vcc, exec

.LBB0_316:
	v_mov_b32_e32 v0, v66
	v_mov_b32_e32 v67, v66
	s_nop 1
	v_permlane32_swap_b32_e32 v0, v67
	v_cmp_gt_u32_e32 vcc, 32, v213
	s_lshl_b64 s[0:1], s[14:15], 8
	s_add_u32 s0, s16, s0
	v_cndmask_b32_e32 v0, v0, v67, vcc
	v_add_f32_e32 v96, v66, v0
	s_addc_u32 s1, s17, s1
	v_lshlrev_b32_e32 v0, 4, v212
	v_lshl_add_u64 v[66:67], s[0:1], 0, v[0:1]
	v_lshlrev_b32_e32 v68, 8, v210
	v_mov_b32_e32 v69, v1
	v_lshl_add_u64 v[66:67], v[66:67], 0, v[68:69]
	s_mov_b64 s[0:1], 0x7000000
	v_lshl_add_u64 v[78:79], v[66:67], 0, s[0:1]
	s_mov_b32 s0, 0x7001000
	v_add_co_u32_e32 v94, vcc, s0, v66
	s_waitcnt vmcnt(0) lgkmcnt(0)
	s_barrier
	s_nop 0
	v_addc_co_u32_e32 v95, vcc, 0, v67, vcc
	global_load_dwordx4 v[66:69], v[94:95], off offset:-4096
	global_load_dwordx4 v[70:73], v[78:79], off offset:1024
	global_load_dwordx4 v[74:77], v[78:79], off offset:2048
	s_nop 0
	global_load_dwordx4 v[78:81], v[78:79], off offset:3072
	s_nop 0
	global_load_dwordx4 v[82:85], v[94:95], off
	global_load_dwordx4 v[86:89], v[94:95], off offset:1024
	global_load_dwordx4 v[90:93], v[94:95], off offset:2048
	global_load_dwordx4 v[98:101], v[94:95], off offset:3072
	s_mulk_i32 s22, 0x2200
	s_add_i32 s0, s22, 0
	v_mul_u32_u24_e32 v94, 0x110, v210
	v_add3_u32 v97, s0, v0, v94
	v_lshlrev_b32_e32 v94, 12, v210
	s_waitcnt vmcnt(0)
	ds_write_b128 v97, v[66:69]
	ds_write_b128 v97, v[70:73] offset:1088
	ds_write_b128 v97, v[74:77] offset:2176
	ds_write_b128 v97, v[78:81] offset:3264
	ds_write_b128 v97, v[82:85] offset:4352
	ds_write_b128 v97, v[86:89] offset:5440
	ds_write_b128 v97, v[90:93] offset:6528
	v_mul_u32_u24_e32 v66, 0x110, v211
	v_add3_u32 v95, s0, v66, v183
	v_div_scale_f32 v102, s[0:1], v96, v96, 1.0
	v_rcp_f32_e32 v103, v102
	ds_write_b128 v97, v[98:101] offset:7616
	s_waitcnt lgkmcnt(0)
	ds_read2_b64 v[98:101], v95 offset1:2
	ds_read2_b64 v[90:93], v95 offset0:4 offset1:6
	ds_read2_b64 v[86:89], v95 offset0:8 offset1:10
	ds_read2_b64 v[82:85], v95 offset0:12 offset1:14
	ds_read2_b64 v[78:81], v95 offset0:16 offset1:18
	ds_read2_b64 v[74:77], v95 offset0:20 offset1:22
	ds_read2_b64 v[70:73], v95 offset0:24 offset1:26
	ds_read2_b64 v[66:69], v95 offset0:28 offset1:30
	v_fma_f32 v104, -v102, v103, 1.0
	v_fmac_f32_e32 v103, v104, v103
	v_div_scale_f32 v104, vcc, 1.0, v96, 1.0
	v_mul_f32_e32 v105, v104, v103
	v_fma_f32 v106, -v102, v105, v104
	v_fmac_f32_e32 v105, v106, v103
	v_fma_f32 v102, -v102, v105, v104
	v_div_fmas_f32 v102, v102, v103, v105
	v_div_fixup_f32 v96, v102, v96, 1.0
	v_pk_mul_f32 v[50:51], v[50:51], v[96:97] op_sel_hi:[1,0]
	s_waitcnt lgkmcnt(0)
	v_lshlrev_b32_e32 v102, 16, v98
	v_and_b32_e32 v103, 0xffff0000, v98
	v_pk_mul_f32 v[52:53], v[52:53], v[96:97] op_sel_hi:[1,0]
	v_lshlrev_b32_e32 v98, 16, v99
	v_and_b32_e32 v99, 0xffff0000, v99
	v_pk_mul_f32 v[50:51], v[50:51], v[102:103]
	v_pk_mul_f32 v[52:53], v[52:53], v[98:99]
	v_cvt_pk_bf16_f32 v50, v50, v51
	v_cvt_pk_bf16_f32 v51, v52, v53
	v_pk_mul_f32 v[52:53], v[54:55], v[96:97] op_sel_hi:[1,0]
	v_lshlrev_b32_e32 v54, 16, v100
	v_and_b32_e32 v55, 0xffff0000, v100
	v_pk_mul_f32 v[52:53], v[52:53], v[54:55]
	v_pk_mul_f32 v[54:55], v[56:57], v[96:97] op_sel_hi:[1,0]
	v_lshlrev_b32_e32 v56, 16, v101
	v_and_b32_e32 v57, 0xffff0000, v101
	v_pk_mul_f32 v[54:55], v[54:55], v[56:57]
	v_cvt_pk_bf16_f32 v52, v52, v53
	v_cvt_pk_bf16_f32 v53, v54, v55
	s_waitcnt lgkmcnt(0)
	ds_write2_b64 v95, v[50:51], v[52:53] offset1:2
	v_pk_mul_f32 v[50:51], v[58:59], v[96:97] op_sel_hi:[1,0]
	v_lshlrev_b32_e32 v52, 16, v90
	v_and_b32_e32 v53, 0xffff0000, v90
	v_pk_mul_f32 v[50:51], v[50:51], v[52:53]
	v_pk_mul_f32 v[52:53], v[60:61], v[96:97] op_sel_hi:[1,0]
	v_lshlrev_b32_e32 v54, 16, v91
	v_and_b32_e32 v55, 0xffff0000, v91
	v_pk_mul_f32 v[52:53], v[52:53], v[54:55]
	v_cvt_pk_bf16_f32 v50, v50, v51
	v_cvt_pk_bf16_f32 v51, v52, v53
	v_pk_mul_f32 v[52:53], v[62:63], v[96:97] op_sel_hi:[1,0]
	v_lshlrev_b32_e32 v54, 16, v92
	v_and_b32_e32 v55, 0xffff0000, v92
	v_pk_mul_f32 v[52:53], v[52:53], v[54:55]
	v_pk_mul_f32 v[54:55], v[64:65], v[96:97] op_sel_hi:[1,0]
	v_lshlrev_b32_e32 v56, 16, v93
	v_and_b32_e32 v57, 0xffff0000, v93
	v_pk_mul_f32 v[54:55], v[54:55], v[56:57]
	v_cvt_pk_bf16_f32 v52, v52, v53
	v_cvt_pk_bf16_f32 v53, v54, v55
	ds_write2_b64 v95, v[50:51], v[52:53] offset0:4 offset1:6
	v_pk_mul_f32 v[34:35], v[34:35], v[96:97] op_sel_hi:[1,0]
	v_lshlrev_b32_e32 v50, 16, v86
	v_and_b32_e32 v51, 0xffff0000, v86
	v_pk_mul_f32 v[34:35], v[34:35], v[50:51]
	v_pk_mul_f32 v[36:37], v[36:37], v[96:97] op_sel_hi:[1,0]
	v_lshlrev_b32_e32 v50, 16, v87
	v_and_b32_e32 v51, 0xffff0000, v87
	v_pk_mul_f32 v[36:37], v[36:37], v[50:51]
	v_cvt_pk_bf16_f32 v34, v34, v35
	v_cvt_pk_bf16_f32 v35, v36, v37
	v_pk_mul_f32 v[36:37], v[38:39], v[96:97] op_sel_hi:[1,0]
	v_lshlrev_b32_e32 v38, 16, v88
	v_and_b32_e32 v39, 0xffff0000, v88
	v_pk_mul_f32 v[36:37], v[36:37], v[38:39]
	v_pk_mul_f32 v[38:39], v[40:41], v[96:97] op_sel_hi:[1,0]
	v_lshlrev_b32_e32 v40, 16, v89
	v_and_b32_e32 v41, 0xffff0000, v89
	v_pk_mul_f32 v[38:39], v[38:39], v[40:41]
	v_cvt_pk_bf16_f32 v36, v36, v37
	v_cvt_pk_bf16_f32 v37, v38, v39
	ds_write2_b64 v95, v[34:35], v[36:37] offset0:8 offset1:10
	v_pk_mul_f32 v[34:35], v[42:43], v[96:97] op_sel_hi:[1,0]
	v_lshlrev_b32_e32 v36, 16, v82
	v_and_b32_e32 v37, 0xffff0000, v82
	v_pk_mul_f32 v[34:35], v[34:35], v[36:37]
	v_pk_mul_f32 v[36:37], v[44:45], v[96:97] op_sel_hi:[1,0]
	v_lshlrev_b32_e32 v38, 16, v83
	v_and_b32_e32 v39, 0xffff0000, v83
	v_pk_mul_f32 v[36:37], v[36:37], v[38:39]
	v_cvt_pk_bf16_f32 v34, v34, v35
	v_cvt_pk_bf16_f32 v35, v36, v37
	v_pk_mul_f32 v[36:37], v[46:47], v[96:97] op_sel_hi:[1,0]
	v_lshlrev_b32_e32 v38, 16, v84
	v_and_b32_e32 v39, 0xffff0000, v84
	v_pk_mul_f32 v[36:37], v[36:37], v[38:39]
	v_pk_mul_f32 v[38:39], v[48:49], v[96:97] op_sel_hi:[1,0]
	v_lshlrev_b32_e32 v40, 16, v85
	v_and_b32_e32 v41, 0xffff0000, v85
	v_pk_mul_f32 v[38:39], v[38:39], v[40:41]
	v_cvt_pk_bf16_f32 v36, v36, v37
	v_cvt_pk_bf16_f32 v37, v38, v39
	ds_write2_b64 v95, v[34:35], v[36:37] offset0:12 offset1:14
	v_pk_mul_f32 v[18:19], v[18:19], v[96:97] op_sel_hi:[1,0]
	v_lshlrev_b32_e32 v34, 16, v78
	v_and_b32_e32 v35, 0xffff0000, v78
	v_pk_mul_f32 v[18:19], v[18:19], v[34:35]
	v_pk_mul_f32 v[20:21], v[20:21], v[96:97] op_sel_hi:[1,0]
	v_lshlrev_b32_e32 v34, 16, v79
	v_and_b32_e32 v35, 0xffff0000, v79
	v_pk_mul_f32 v[20:21], v[20:21], v[34:35]
	v_cvt_pk_bf16_f32 v18, v18, v19
	v_cvt_pk_bf16_f32 v19, v20, v21
	v_pk_mul_f32 v[20:21], v[22:23], v[96:97] op_sel_hi:[1,0]
	v_lshlrev_b32_e32 v22, 16, v80
	v_and_b32_e32 v23, 0xffff0000, v80
	v_pk_mul_f32 v[20:21], v[20:21], v[22:23]
	v_pk_mul_f32 v[22:23], v[24:25], v[96:97] op_sel_hi:[1,0]
	v_lshlrev_b32_e32 v24, 16, v81
	v_and_b32_e32 v25, 0xffff0000, v81
	v_pk_mul_f32 v[22:23], v[22:23], v[24:25]
	v_cvt_pk_bf16_f32 v20, v20, v21
	v_cvt_pk_bf16_f32 v21, v22, v23
	ds_write2_b64 v95, v[18:19], v[20:21] offset0:16 offset1:18
	v_pk_mul_f32 v[18:19], v[26:27], v[96:97] op_sel_hi:[1,0]
	v_lshlrev_b32_e32 v20, 16, v74
	v_and_b32_e32 v21, 0xffff0000, v74
	v_pk_mul_f32 v[18:19], v[18:19], v[20:21]
	v_pk_mul_f32 v[20:21], v[28:29], v[96:97] op_sel_hi:[1,0]
	v_lshlrev_b32_e32 v22, 16, v75
	v_and_b32_e32 v23, 0xffff0000, v75
	v_pk_mul_f32 v[20:21], v[20:21], v[22:23]
	v_cvt_pk_bf16_f32 v18, v18, v19
	v_cvt_pk_bf16_f32 v19, v20, v21
	v_pk_mul_f32 v[20:21], v[30:31], v[96:97] op_sel_hi:[1,0]
	v_lshlrev_b32_e32 v22, 16, v76
	v_and_b32_e32 v23, 0xffff0000, v76
	v_pk_mul_f32 v[20:21], v[20:21], v[22:23]
	v_pk_mul_f32 v[22:23], v[32:33], v[96:97] op_sel_hi:[1,0]
	v_lshlrev_b32_e32 v24, 16, v77
	v_and_b32_e32 v25, 0xffff0000, v77
	v_pk_mul_f32 v[22:23], v[22:23], v[24:25]
	v_cvt_pk_bf16_f32 v20, v20, v21
	v_cvt_pk_bf16_f32 v21, v22, v23
	ds_write2_b64 v95, v[18:19], v[20:21] offset0:20 offset1:22
	v_pk_mul_f32 v[2:3], v[2:3], v[96:97] op_sel_hi:[1,0]
	v_lshlrev_b32_e32 v18, 16, v70
	v_and_b32_e32 v19, 0xffff0000, v70
	v_pk_mul_f32 v[2:3], v[2:3], v[18:19]
	v_pk_mul_f32 v[4:5], v[4:5], v[96:97] op_sel_hi:[1,0]
	v_lshlrev_b32_e32 v18, 16, v71
	v_and_b32_e32 v19, 0xffff0000, v71
	v_pk_mul_f32 v[4:5], v[4:5], v[18:19]
	v_cvt_pk_bf16_f32 v2, v2, v3
	v_cvt_pk_bf16_f32 v3, v4, v5
	v_pk_mul_f32 v[4:5], v[6:7], v[96:97] op_sel_hi:[1,0]
	v_lshlrev_b32_e32 v6, 16, v72
	v_and_b32_e32 v7, 0xffff0000, v72
	v_pk_mul_f32 v[4:5], v[4:5], v[6:7]
	v_pk_mul_f32 v[6:7], v[8:9], v[96:97] op_sel_hi:[1,0]
	v_lshlrev_b32_e32 v8, 16, v73
	v_and_b32_e32 v9, 0xffff0000, v73
	v_pk_mul_f32 v[6:7], v[6:7], v[8:9]
	v_cvt_pk_bf16_f32 v4, v4, v5
	v_cvt_pk_bf16_f32 v5, v6, v7
	ds_write2_b64 v95, v[2:3], v[4:5] offset0:24 offset1:26
	v_pk_mul_f32 v[2:3], v[10:11], v[96:97] op_sel_hi:[1,0]
	v_lshlrev_b32_e32 v4, 16, v66
	v_and_b32_e32 v5, 0xffff0000, v66
	v_pk_mul_f32 v[2:3], v[2:3], v[4:5]
	v_pk_mul_f32 v[4:5], v[12:13], v[96:97] op_sel_hi:[1,0]
	v_lshlrev_b32_e32 v6, 16, v67
	v_and_b32_e32 v7, 0xffff0000, v67
	v_pk_mul_f32 v[4:5], v[4:5], v[6:7]
	s_lshl_b64 s[0:1], s[14:15], 12
	v_cvt_pk_bf16_f32 v2, v2, v3
	v_cvt_pk_bf16_f32 v3, v4, v5
	v_pk_mul_f32 v[4:5], v[14:15], v[96:97] op_sel_hi:[1,0]
	v_lshlrev_b32_e32 v6, 16, v68
	v_and_b32_e32 v7, 0xffff0000, v68
	s_add_u32 s0, s33, s0
	v_pk_mul_f32 v[4:5], v[4:5], v[6:7]
	v_pk_mul_f32 v[6:7], v[16:17], v[96:97] op_sel_hi:[1,0]
	v_lshlrev_b32_e32 v8, 16, v69
	v_and_b32_e32 v9, 0xffff0000, v69
	s_addc_u32 s1, s64, s1
	s_lshl_b32 s2, s96, 8
	v_pk_mul_f32 v[6:7], v[6:7], v[8:9]
	s_add_u32 s0, s0, s2
	v_cvt_pk_bf16_f32 v4, v4, v5
	v_cvt_pk_bf16_f32 v5, v6, v7
	s_addc_u32 s1, s1, 0
	ds_write2_b64 v95, v[2:3], v[4:5] offset0:28 offset1:30
	v_lshl_add_u64 v[2:3], s[0:1], 0, v[0:1]
	s_mov_b64 s[0:1], 0x800
	s_waitcnt lgkmcnt(0)
	v_lshl_add_u64 v[6:7], v[2:3], 0, s[0:1]
	v_mov_b32_e32 v95, v1
	ds_read_b128 v[2:5], v97
	v_lshl_add_u64 v[8:9], v[6:7], 0, v[94:95]
	s_waitcnt lgkmcnt(0)
	global_store_dwordx4 v[8:9], v[2:5], off sc1
	s_nop 1
	v_or_b32_e32 v0, 0x4000, v94
	ds_read_b128 v[2:5], v97 offset:1088
	v_lshl_add_u64 v[8:9], v[6:7], 0, v[0:1]
	s_waitcnt lgkmcnt(0)
	global_store_dwordx4 v[8:9], v[2:5], off sc1
	s_nop 1
	v_or_b32_e32 v0, 0x8000, v94
	ds_read_b128 v[2:5], v97 offset:2176
	v_lshl_add_u64 v[8:9], v[6:7], 0, v[0:1]
	s_waitcnt lgkmcnt(0)
	global_store_dwordx4 v[8:9], v[2:5], off sc1
	s_nop 1
	v_or_b32_e32 v0, 0xc000, v94
	ds_read_b128 v[2:5], v97 offset:3264
	v_lshl_add_u64 v[8:9], v[6:7], 0, v[0:1]
	s_waitcnt lgkmcnt(0)
	global_store_dwordx4 v[8:9], v[2:5], off sc1
	s_nop 1
	v_or_b32_e32 v0, 0x10000, v94
	ds_read_b128 v[2:5], v97 offset:4352
	v_lshl_add_u64 v[8:9], v[6:7], 0, v[0:1]
	s_waitcnt lgkmcnt(0)
	global_store_dwordx4 v[8:9], v[2:5], off sc1
	s_nop 1
	v_or_b32_e32 v0, 0x14000, v94
	ds_read_b128 v[2:5], v97 offset:5440
	v_lshl_add_u64 v[8:9], v[6:7], 0, v[0:1]
	s_waitcnt lgkmcnt(0)
	global_store_dwordx4 v[8:9], v[2:5], off sc1
	s_nop 1
	v_or_b32_e32 v0, 0x18000, v94
	ds_read_b128 v[2:5], v97 offset:6528
	v_lshl_add_u64 v[8:9], v[6:7], 0, v[0:1]
	s_waitcnt lgkmcnt(0)
	global_store_dwordx4 v[8:9], v[2:5], off sc1
	s_nop 1
	v_or_b32_e32 v0, 0x1c000, v94
	ds_read_b128 v[2:5], v97 offset:7616
	v_lshl_add_u64 v[6:7], v[6:7], 0, v[0:1]
	s_waitcnt lgkmcnt(0)
	global_store_dwordx4 v[6:7], v[2:5], off sc1
	s_nop 1
	s_andn2_b64 vcc, exec, s[94:95]
	s_cbranch_vccnz .Lpre_skip_m1
	s_mov_b32 s32, 1
	s_lshl_b32 s2, s97, 8
	s_add_u32 s2, s86, s2
	s_addc_u32 s3, s87, 0
	s_and_saveexec_b64 s[0:1], s[10:11]
	global_atomic_add v10, v1, v254, s[2:3] sc0
	s_or_b64 exec, exec, s[0:1]
.Lpre_skip_m1:
	s_waitcnt vmcnt(0)
	s_barrier
	v_cmp_eq_u32_e64 s[0:1], 0, v182
	s_branch .LBB0_339

.LBB0_338:
	s_lshl_b64 s[2:3], s[0:1], 8
	s_add_u32 s2, s58, s2
	s_addc_u32 s3, s59, s3
	v_lshlrev_b32_e32 v0, 4, v192
	v_lshl_add_u64 v[66:67], s[2:3], 0, v[0:1]
	v_lshlrev_b32_e32 v68, 1, v224
	v_mov_b32_e32 v69, v1
	v_lshl_add_u64 v[66:67], v[66:67], 0, v[68:69]
	s_mov_b64 s[2:3], 0x3000000
	v_lshl_add_u64 v[78:79], v[66:67], 0, s[2:3]
	s_mov_b32 s2, 0x3001000
	v_add_co_u32_e32 v86, vcc, s2, v66
	s_waitcnt vmcnt(0) lgkmcnt(0)
	s_barrier
	s_nop 0
	v_addc_co_u32_e32 v87, vcc, 0, v67, vcc
	global_load_dwordx4 v[66:69], v[86:87], off offset:-4096
	global_load_dwordx4 v[70:73], v[78:79], off offset:1024
	global_load_dwordx4 v[74:77], v[78:79], off offset:2048
	s_nop 0
	global_load_dwordx4 v[78:81], v[78:79], off offset:3072
	s_nop 0
	global_load_dwordx4 v[82:85], v[86:87], off
	global_load_dwordx4 v[90:93], v[86:87], off offset:1024
	global_load_dwordx4 v[94:97], v[86:87], off offset:2048
	global_load_dwordx4 v[98:101], v[86:87], off offset:3072
	s_mulk_i32 s56, 0x2200
	v_mul_u32_u24_e32 v87, 0x110, v191
	s_add_i32 s2, s56, 0
	v_add3_u32 v88, s2, v0, v87
	v_mul_u32_u24_e32 v89, 0x110, v193
	v_add3_u32 v87, s2, v89, v194
	s_lshl_b64 s[0:1], s[0:1], 12
	s_add_u32 s0, s33, s0
	s_addc_u32 s1, s64, s1
	s_lshl_b32 s2, s96, 8
	s_add_u32 s0, s0, s2
	s_addc_u32 s1, s1, 0
	v_lshlrev_b32_e32 v86, 12, v191
	s_waitcnt vmcnt(0)
	ds_write_b128 v88, v[66:69]
	ds_write_b128 v88, v[70:73] offset:1088
	ds_write_b128 v88, v[74:77] offset:2176
	ds_write_b128 v88, v[78:81] offset:3264
	ds_write_b128 v88, v[82:85] offset:4352
	ds_write_b128 v88, v[90:93] offset:5440
	ds_write_b128 v88, v[94:97] offset:6528
	ds_write_b128 v88, v[98:101] offset:7616
	s_waitcnt lgkmcnt(0)
	ds_read2_b64 v[90:93], v87 offset1:2
	ds_read2_b64 v[94:97], v87 offset0:4 offset1:6
	ds_read2_b64 v[98:101], v87 offset0:8 offset1:10
	ds_read2_b64 v[82:85], v87 offset0:12 offset1:14
	ds_read2_b64 v[78:81], v87 offset0:16 offset1:18
	ds_read2_b64 v[74:77], v87 offset0:20 offset1:22
	ds_read2_b64 v[70:73], v87 offset0:24 offset1:26
	ds_read2_b64 v[66:69], v87 offset0:28 offset1:30
	s_waitcnt lgkmcnt(5)
	v_lshlrev_b32_e32 v110, 16, v98
	v_and_b32_e32 v111, 0xffff0000, v98
	v_lshlrev_b32_e32 v98, 16, v99
	v_and_b32_e32 v99, 0xffff0000, v99
	v_lshlrev_b32_e32 v112, 16, v100
	v_and_b32_e32 v113, 0xffff0000, v100
	v_pk_mul_f32 v[34:35], v[34:35], v[110:111]
	v_pk_mul_f32 v[36:37], v[36:37], v[98:99]
	v_pk_mul_f32 v[38:39], v[38:39], v[112:113]
	v_lshlrev_b32_e32 v102, 16, v90
	v_and_b32_e32 v103, 0xffff0000, v90
	v_lshlrev_b32_e32 v90, 16, v91
	v_and_b32_e32 v91, 0xffff0000, v91
	v_lshlrev_b32_e32 v104, 16, v92
	v_and_b32_e32 v105, 0xffff0000, v92
	v_lshlrev_b32_e32 v92, 16, v93
	v_and_b32_e32 v93, 0xffff0000, v93
	v_cvt_pk_bf16_f32 v34, v34, v35
	v_cvt_pk_bf16_f32 v35, v36, v37
	v_cvt_pk_bf16_f32 v36, v38, v39
	v_lshlrev_b32_e32 v38, 16, v101
	v_and_b32_e32 v39, 0xffff0000, v101
	v_lshlrev_b32_e32 v106, 16, v94
	v_and_b32_e32 v107, 0xffff0000, v94
	v_lshlrev_b32_e32 v94, 16, v95
	v_and_b32_e32 v95, 0xffff0000, v95
	v_lshlrev_b32_e32 v108, 16, v96
	v_and_b32_e32 v109, 0xffff0000, v96
	v_lshlrev_b32_e32 v96, 16, v97
	v_and_b32_e32 v97, 0xffff0000, v97
	v_pk_mul_f32 v[50:51], v[50:51], v[102:103]
	v_pk_mul_f32 v[52:53], v[52:53], v[90:91]
	v_pk_mul_f32 v[54:55], v[54:55], v[104:105]
	v_pk_mul_f32 v[56:57], v[56:57], v[92:93]
	v_pk_mul_f32 v[38:39], v[40:41], v[38:39]
	v_pk_mul_f32 v[58:59], v[58:59], v[106:107]
	v_pk_mul_f32 v[60:61], v[60:61], v[94:95]
	v_pk_mul_f32 v[62:63], v[62:63], v[108:109]
	v_pk_mul_f32 v[64:65], v[64:65], v[96:97]
	v_cvt_pk_bf16_f32 v50, v50, v51
	v_cvt_pk_bf16_f32 v51, v52, v53
	v_cvt_pk_bf16_f32 v52, v54, v55
	v_cvt_pk_bf16_f32 v53, v56, v57
	v_cvt_pk_bf16_f32 v37, v38, v39
	s_waitcnt lgkmcnt(0)
	v_cvt_pk_bf16_f32 v54, v58, v59
	v_cvt_pk_bf16_f32 v55, v60, v61
	v_cvt_pk_bf16_f32 v56, v62, v63
	v_cvt_pk_bf16_f32 v57, v64, v65
	ds_write2_b64 v87, v[50:51], v[52:53] offset1:2
	ds_write2_b64 v87, v[54:55], v[56:57] offset0:4 offset1:6
	ds_write2_b64 v87, v[34:35], v[36:37] offset0:8 offset1:10
	s_waitcnt lgkmcnt(7)
	v_lshlrev_b32_e32 v34, 16, v82
	v_and_b32_e32 v35, 0xffff0000, v82
	v_lshlrev_b32_e32 v36, 16, v83
	v_and_b32_e32 v37, 0xffff0000, v83
	v_pk_mul_f32 v[34:35], v[42:43], v[34:35]
	v_pk_mul_f32 v[36:37], v[44:45], v[36:37]
	v_cvt_pk_bf16_f32 v34, v34, v35
	v_cvt_pk_bf16_f32 v35, v36, v37
	v_lshlrev_b32_e32 v36, 16, v84
	v_and_b32_e32 v37, 0xffff0000, v84
	v_lshlrev_b32_e32 v38, 16, v85
	v_and_b32_e32 v39, 0xffff0000, v85
	v_pk_mul_f32 v[36:37], v[46:47], v[36:37]
	v_pk_mul_f32 v[38:39], v[48:49], v[38:39]
	v_cvt_pk_bf16_f32 v36, v36, v37
	v_cvt_pk_bf16_f32 v37, v38, v39
	ds_write2_b64 v87, v[34:35], v[36:37] offset0:12 offset1:14
	s_waitcnt lgkmcnt(7)
	v_lshlrev_b32_e32 v34, 16, v78
	v_and_b32_e32 v35, 0xffff0000, v78
	v_pk_mul_f32 v[18:19], v[18:19], v[34:35]
	v_lshlrev_b32_e32 v34, 16, v79
	v_and_b32_e32 v35, 0xffff0000, v79
	v_pk_mul_f32 v[20:21], v[20:21], v[34:35]
	v_cvt_pk_bf16_f32 v18, v18, v19
	v_cvt_pk_bf16_f32 v19, v20, v21
	v_lshlrev_b32_e32 v20, 16, v80
	v_and_b32_e32 v21, 0xffff0000, v80
	v_pk_mul_f32 v[20:21], v[22:23], v[20:21]
	v_lshlrev_b32_e32 v22, 16, v81
	v_and_b32_e32 v23, 0xffff0000, v81
	v_pk_mul_f32 v[22:23], v[24:25], v[22:23]
	v_cvt_pk_bf16_f32 v20, v20, v21
	v_cvt_pk_bf16_f32 v21, v22, v23
	ds_write2_b64 v87, v[18:19], v[20:21] offset0:16 offset1:18
	s_waitcnt lgkmcnt(7)
	v_lshlrev_b32_e32 v18, 16, v74
	v_and_b32_e32 v19, 0xffff0000, v74
	v_lshlrev_b32_e32 v20, 16, v75
	v_and_b32_e32 v21, 0xffff0000, v75
	v_pk_mul_f32 v[18:19], v[26:27], v[18:19]
	v_pk_mul_f32 v[20:21], v[28:29], v[20:21]
	v_cvt_pk_bf16_f32 v18, v18, v19
	v_cvt_pk_bf16_f32 v19, v20, v21
	v_lshlrev_b32_e32 v20, 16, v76
	v_and_b32_e32 v21, 0xffff0000, v76
	v_lshlrev_b32_e32 v22, 16, v77
	v_and_b32_e32 v23, 0xffff0000, v77
	v_pk_mul_f32 v[20:21], v[30:31], v[20:21]
	v_pk_mul_f32 v[22:23], v[32:33], v[22:23]
	v_cvt_pk_bf16_f32 v20, v20, v21
	v_cvt_pk_bf16_f32 v21, v22, v23
	ds_write2_b64 v87, v[18:19], v[20:21] offset0:20 offset1:22
	s_waitcnt lgkmcnt(7)
	v_lshlrev_b32_e32 v18, 16, v70
	v_and_b32_e32 v19, 0xffff0000, v70
	v_pk_mul_f32 v[2:3], v[2:3], v[18:19]
	v_lshlrev_b32_e32 v18, 16, v71
	v_and_b32_e32 v19, 0xffff0000, v71
	v_pk_mul_f32 v[4:5], v[4:5], v[18:19]
	v_cvt_pk_bf16_f32 v2, v2, v3
	v_cvt_pk_bf16_f32 v3, v4, v5
	v_lshlrev_b32_e32 v4, 16, v72
	v_and_b32_e32 v5, 0xffff0000, v72
	v_pk_mul_f32 v[4:5], v[6:7], v[4:5]
	v_lshlrev_b32_e32 v6, 16, v73
	v_and_b32_e32 v7, 0xffff0000, v73
	v_pk_mul_f32 v[6:7], v[8:9], v[6:7]
	v_cvt_pk_bf16_f32 v4, v4, v5
	v_cvt_pk_bf16_f32 v5, v6, v7
	ds_write2_b64 v87, v[2:3], v[4:5] offset0:24 offset1:26
	s_waitcnt lgkmcnt(7)
	v_lshlrev_b32_e32 v2, 16, v66
	v_and_b32_e32 v3, 0xffff0000, v66
	v_lshlrev_b32_e32 v4, 16, v67
	v_and_b32_e32 v5, 0xffff0000, v67
	v_pk_mul_f32 v[2:3], v[10:11], v[2:3]
	v_pk_mul_f32 v[4:5], v[12:13], v[4:5]
	v_cvt_pk_bf16_f32 v2, v2, v3
	v_cvt_pk_bf16_f32 v3, v4, v5
	v_lshlrev_b32_e32 v4, 16, v68
	v_and_b32_e32 v5, 0xffff0000, v68
	v_lshlrev_b32_e32 v6, 16, v69
	v_and_b32_e32 v7, 0xffff0000, v69
	v_pk_mul_f32 v[4:5], v[14:15], v[4:5]
	v_pk_mul_f32 v[6:7], v[16:17], v[6:7]
	v_cvt_pk_bf16_f32 v4, v4, v5
	v_cvt_pk_bf16_f32 v5, v6, v7
	ds_write2_b64 v87, v[2:3], v[4:5] offset0:28 offset1:30
	s_waitcnt lgkmcnt(0)
	v_lshl_add_u64 v[6:7], s[0:1], 0, v[0:1]
	v_mov_b32_e32 v87, v1
	ds_read_b128 v[2:5], v88
	v_lshl_add_u64 v[8:9], v[6:7], 0, v[86:87]
	s_waitcnt lgkmcnt(0)
	global_store_dwordx4 v[8:9], v[2:5], off sc1
	s_nop 1
	v_or_b32_e32 v0, 0x4000, v86
	ds_read_b128 v[2:5], v88 offset:1088
	v_lshl_add_u64 v[8:9], v[6:7], 0, v[0:1]
	s_waitcnt lgkmcnt(0)
	global_store_dwordx4 v[8:9], v[2:5], off sc1
	s_nop 1
	v_or_b32_e32 v0, 0x8000, v86
	ds_read_b128 v[2:5], v88 offset:2176
	v_lshl_add_u64 v[8:9], v[6:7], 0, v[0:1]
	s_waitcnt lgkmcnt(0)
	global_store_dwordx4 v[8:9], v[2:5], off sc1
	s_nop 1
	v_or_b32_e32 v0, 0xc000, v86
	ds_read_b128 v[2:5], v88 offset:3264
	v_lshl_add_u64 v[8:9], v[6:7], 0, v[0:1]
	s_waitcnt lgkmcnt(0)
	global_store_dwordx4 v[8:9], v[2:5], off sc1
	s_nop 1
	v_or_b32_e32 v0, 0x10000, v86
	ds_read_b128 v[2:5], v88 offset:4352
	v_lshl_add_u64 v[8:9], v[6:7], 0, v[0:1]
	s_waitcnt lgkmcnt(0)
	global_store_dwordx4 v[8:9], v[2:5], off sc1
	s_nop 1
	v_or_b32_e32 v0, 0x14000, v86
	ds_read_b128 v[2:5], v88 offset:5440
	v_lshl_add_u64 v[8:9], v[6:7], 0, v[0:1]
	s_waitcnt lgkmcnt(0)
	global_store_dwordx4 v[8:9], v[2:5], off sc1
	s_nop 1
	v_or_b32_e32 v0, 0x18000, v86
	ds_read_b128 v[2:5], v88 offset:6528
	v_lshl_add_u64 v[8:9], v[6:7], 0, v[0:1]
	s_waitcnt lgkmcnt(0)
	global_store_dwordx4 v[8:9], v[2:5], off sc1
	s_nop 1
	v_or_b32_e32 v0, 0x1c000, v86
	ds_read_b128 v[2:5], v88 offset:7616
	v_lshl_add_u64 v[6:7], v[6:7], 0, v[0:1]
	s_waitcnt lgkmcnt(0)
	global_store_dwordx4 v[6:7], v[2:5], off sc1
	s_nop 1
	s_andn2_b64 vcc, exec, s[94:95]
	s_cbranch_vccnz .Lpre_skip_m0
	s_mov_b32 s32, 1
	s_lshl_b32 s2, s97, 8
	s_add_u32 s2, s86, s2
	s_addc_u32 s3, s87, 0
	s_and_saveexec_b64 s[0:1], s[10:11]
	global_atomic_add v10, v1, v254, s[2:3] sc0
	s_or_b64 exec, exec, s[0:1]
.Lpre_skip_m0:
	s_waitcnt vmcnt(0)
	v_cmp_eq_u32_e64 s[0:1], 0, v190
	s_barrier

.LBB0_375:
	v_and_b32_e32 v17, 15, v16
	v_bfe_u32 v172, v16, 4, 2
	v_lshlrev_b32_e32 v16, 4, v172
	v_lshlrev_b32_e32 v173, 2, v17
	s_and_b32 s5, s11, 3
	v_lshl_or_b32 v140, s20, 6, v17
	v_lshl_or_b32 v16, v17, 6, v16
	s_lshl_b32 s11, s20, 13
	v_and_b32_e32 v17, 32, v173
	s_add_i32 m0, s19, 0x18000
	v_lshl_add_u64 v[2:3], v[2:3], 0, s[68:69]
	v_bitop3_b32 v18, v16, s11, v17 bitop3:0xde
	s_lshl_b32 s11, s5, 12
	s_waitcnt vmcnt(2)
	s_barrier
	global_load_lds_dwordx4 v[2:3], off
	v_lshl_add_u64 v[2:3], v[4:5], 0, s[68:69]
	s_add_i32 m0, s19, 0x1a000
	s_add_i32 s20, s19, 0x8000
	s_add_i32 s21, s19, 0xa000
	global_load_lds_dwordx4 v[2:3], off
	v_lshl_add_u64 v[2:3], v[8:9], 0, s[68:69]
	s_mov_b32 m0, s20
	s_add_u32 s22, s2, 0x80080
	global_load_lds_dwordx4 v[2:3], off
	v_lshl_add_u64 v[2:3], v[6:7], 0, s[68:69]
	s_mov_b32 m0, s21
	s_addc_u32 s23, s3, 0
	global_load_lds_dwordx4 v[2:3], off
	s_add_i32 m0, s19, 0x1c000
	v_lshl_add_u64 v[2:3], s[22:23], 0, v[0:1]
	global_load_lds_dwordx4 v[2:3], off
	v_lshl_add_u64 v[2:3], s[22:23], 0, v[130:131]
	s_add_i32 m0, s19, 0x1e000
	s_add_u32 s22, s56, s12
	global_load_lds_dwordx4 v[2:3], off
	v_lshlrev_b32_e32 v2, 15, v10
	v_and_b32_e32 v2, 0xffff0000, v2
	v_lshl_add_u32 v2, v12, 12, v2
	v_and_b32_e32 v3, 1, v10
	v_bitop3_b32 v141, v16, s11, v17 bitop3:0xde
	s_addc_u32 s23, s57, s13
	s_ashr_i32 s11, s10, 31
	v_lshl_or_b32 v2, v3, 6, v2
	s_lshl_b64 s[10:11], s[10:11], 20
	v_lshl_add_u32 v2, v13, 1, v2
	v_mov_b32_e32 v3, v1
	s_lshl_b64 s[12:13], s[8:9], 18
	v_lshl_add_u64 v[2:3], s[10:11], 0, v[2:3]
	s_and_b32 s8, s13, 0x3ffff
	s_and_b32 s12, s12, 0xfff00000
	v_mov_b32_e32 v4, s8
	v_subrev_co_u32_e32 v2, vcc, s12, v2
	v_readlane_b32 s26, v255, 20
	s_nop 0
	v_subb_co_u32_e32 v3, vcc, v3, v4, vcc
	v_readlane_b32 s27, v255, 21
	s_and_b32 s8, s9, 1
	s_lshl_b32 s8, s8, 22
	v_lshl_add_u64 v[136:137], s[26:27], 0, v[2:3]
	v_lshlrev_b32_e32 v2, 15, v11
	v_and_b32_e32 v2, 0xffff0000, v2
	v_lshl_add_u32 v2, v14, 12, v2
	v_and_b32_e32 v3, 1, v11
	v_lshl_or_b32 v2, v3, 6, v2
	v_lshl_add_u32 v2, v15, 1, v2
	v_mov_b32_e32 v3, v1
	v_lshl_add_u64 v[2:3], s[10:11], 0, v[2:3]
	v_subrev_co_u32_e32 v2, vcc, s12, v2
	s_lshl_b32 s9, s24, 20
	s_waitcnt vmcnt(6)
	s_nop 0
	v_subb_co_u32_e32 v3, vcc, v3, v4, vcc
	s_or_b32 s8, s8, s9
	v_lshl_add_u64 v[138:139], s[26:27], 0, v[2:3]
	s_add_u32 s24, s30, s8
	v_mov_b32_e32 v2, 0
	s_addc_u32 s25, s31, 0
	s_mov_b32 s26, -2
	s_mov_b64 s[8:9], 0
	v_add_u32_e32 v142, 0, v18
	v_mov_b32_e32 v3, v2
	v_mov_b32_e32 v4, v2
	v_mov_b32_e32 v5, v2
	v_mov_b32_e32 v6, v2
	v_mov_b32_e32 v7, v2
	v_mov_b32_e32 v8, v2
	v_mov_b32_e32 v9, v2
	v_mov_b32_e32 v18, v2
	v_mov_b32_e32 v19, v2
	v_mov_b32_e32 v20, v2
	v_mov_b32_e32 v21, v2
	v_mov_b32_e32 v22, v2
	v_mov_b32_e32 v23, v2
	v_mov_b32_e32 v24, v2
	v_mov_b32_e32 v25, v2
	v_mov_b32_e32 v34, v2
	v_mov_b32_e32 v35, v2
	v_mov_b32_e32 v36, v2
	v_mov_b32_e32 v37, v2
	v_mov_b32_e32 v38, v2
	v_mov_b32_e32 v39, v2
	v_mov_b32_e32 v40, v2
	v_mov_b32_e32 v41, v2
	v_mov_b32_e32 v50, v2
	v_mov_b32_e32 v51, v2
	v_mov_b32_e32 v52, v2
	v_mov_b32_e32 v53, v2
	v_mov_b32_e32 v54, v2
	v_mov_b32_e32 v55, v2
	v_mov_b32_e32 v56, v2
	v_mov_b32_e32 v57, v2
	v_mov_b32_e32 v10, v2
	v_mov_b32_e32 v11, v2
	v_mov_b32_e32 v12, v2
	v_mov_b32_e32 v13, v2
	v_mov_b32_e32 v14, v2
	v_mov_b32_e32 v15, v2
	v_mov_b32_e32 v16, v2
	v_mov_b32_e32 v17, v2
	v_mov_b32_e32 v26, v2
	v_mov_b32_e32 v27, v2
	v_mov_b32_e32 v28, v2
	v_mov_b32_e32 v29, v2
	v_mov_b32_e32 v30, v2
	v_mov_b32_e32 v31, v2
	v_mov_b32_e32 v32, v2
	v_mov_b32_e32 v33, v2
	v_mov_b32_e32 v42, v2
	v_mov_b32_e32 v43, v2
	v_mov_b32_e32 v44, v2
	v_mov_b32_e32 v45, v2
	v_mov_b32_e32 v46, v2
	v_mov_b32_e32 v47, v2
	v_mov_b32_e32 v48, v2
	v_mov_b32_e32 v49, v2
	v_mov_b32_e32 v58, v2
	v_mov_b32_e32 v59, v2
	v_mov_b32_e32 v60, v2
	v_mov_b32_e32 v61, v2
	v_mov_b32_e32 v62, v2
	v_mov_b32_e32 v63, v2
	v_mov_b32_e32 v64, v2
	v_mov_b32_e32 v65, v2
	v_mov_b32_e32 v66, v2
	v_mov_b32_e32 v67, v2
	v_mov_b32_e32 v68, v2
	v_mov_b32_e32 v69, v2
	v_mov_b32_e32 v70, v2
	v_mov_b32_e32 v71, v2
	v_mov_b32_e32 v72, v2
	v_mov_b32_e32 v73, v2
	v_mov_b32_e32 v82, v2
	v_mov_b32_e32 v83, v2
	v_mov_b32_e32 v84, v2
	v_mov_b32_e32 v85, v2
	v_mov_b32_e32 v86, v2
	v_mov_b32_e32 v87, v2
	v_mov_b32_e32 v88, v2
	v_mov_b32_e32 v89, v2
	v_mov_b32_e32 v98, v2
	v_mov_b32_e32 v99, v2
	v_mov_b32_e32 v100, v2
	v_mov_b32_e32 v101, v2
	v_mov_b32_e32 v102, v2
	v_mov_b32_e32 v103, v2
	v_mov_b32_e32 v104, v2
	v_mov_b32_e32 v105, v2
	v_mov_b32_e32 v114, v2
	v_mov_b32_e32 v115, v2
	v_mov_b32_e32 v116, v2
	v_mov_b32_e32 v117, v2
	v_mov_b32_e32 v118, v2
	v_mov_b32_e32 v119, v2
	v_mov_b32_e32 v120, v2
	v_mov_b32_e32 v121, v2
	v_mov_b32_e32 v74, v2
	v_mov_b32_e32 v75, v2
	v_mov_b32_e32 v76, v2
	v_mov_b32_e32 v77, v2
	v_mov_b32_e32 v78, v2
	v_mov_b32_e32 v79, v2
	v_mov_b32_e32 v80, v2
	v_mov_b32_e32 v81, v2
	v_mov_b32_e32 v90, v2
	v_mov_b32_e32 v91, v2
	v_mov_b32_e32 v92, v2
	v_mov_b32_e32 v93, v2
	v_mov_b32_e32 v94, v2
	v_mov_b32_e32 v95, v2
	v_mov_b32_e32 v96, v2
	v_mov_b32_e32 v97, v2
	v_mov_b32_e32 v106, v2
	v_mov_b32_e32 v107, v2
	v_mov_b32_e32 v108, v2
	v_mov_b32_e32 v109, v2
	v_mov_b32_e32 v110, v2
	v_mov_b32_e32 v111, v2
	v_mov_b32_e32 v112, v2
	v_mov_b32_e32 v113, v2
	v_mov_b32_e32 v122, v2
	v_mov_b32_e32 v123, v2
	v_mov_b32_e32 v124, v2
	v_mov_b32_e32 v125, v2
	v_mov_b32_e32 v126, v2
	v_mov_b32_e32 v127, v2
	v_mov_b32_e32 v128, v2
	v_mov_b32_e32 v129, v2
	s_barrier
	.p2alignl 6, 3212836864

.LBB0_379:
	v_lshlrev_b32_e32 v0, 3, v172
	v_lshl_or_b32 v0, s5, 5, v0
	v_lshl_add_u32 v164, s0, 8, v140
	v_lshl_or_b32 v174, s16, 8, v0
	v_lshlrev_b32_e32 v0, 1, v174
	v_ashrrev_i32_e32 v165, 31, v164
	v_lshl_add_u64 v[166:167], s[44:45], 0, v[0:1]
	v_lshlrev_b64 v[130:131], 12, v[164:165]
	v_or_b32_e32 v162, 16, v164
	v_lshl_add_u64 v[130:131], v[166:167], 0, v[130:131]
	v_ashrrev_i32_e32 v163, 31, v162
	global_load_dwordx4 v[176:179], v[130:131], off
	global_load_dwordx4 v[154:157], v[130:131], off offset:256
	v_lshlrev_b64 v[130:131], 12, v[162:163]
	v_or_b32_e32 v160, 32, v164
	v_lshl_add_u64 v[130:131], v[166:167], 0, v[130:131]
	v_ashrrev_i32_e32 v161, 31, v160
	global_load_dwordx4 v[150:153], v[130:131], off
	global_load_dwordx4 v[146:149], v[130:131], off offset:256
	v_lshlrev_b64 v[130:131], 12, v[160:161]
	v_or_b32_e32 v158, 48, v164
	v_lshl_add_u64 v[130:131], v[166:167], 0, v[130:131]
	v_ashrrev_i32_e32 v159, 31, v158
	global_load_dwordx4 v[142:145], v[130:131], off
	global_load_dwordx4 v[138:141], v[130:131], off offset:256
	v_lshlrev_b64 v[130:131], 12, v[158:159]
	v_lshl_add_u64 v[130:131], v[166:167], 0, v[130:131]
	global_load_dwordx4 v[134:137], v[130:131], off
	s_nop 0
	global_load_dwordx4 v[130:133], v[130:131], off offset:256
	v_add_u32_e32 v218, 0x80, v164
	v_ashrrev_i32_e32 v219, 31, v218
	v_lshlrev_b64 v[220:221], 12, v[218:219]
	v_lshl_add_u64 v[220:221], v[166:167], 0, v[220:221]
	global_load_dwordx4 v[184:187], v[220:221], off
	global_load_dwordx4 v[188:191], v[220:221], off offset:256
	v_add_u32_e32 v218, 0x90, v164
	v_ashrrev_i32_e32 v219, 31, v218
	v_lshlrev_b64 v[220:221], 12, v[218:219]
	v_lshl_add_u64 v[220:221], v[166:167], 0, v[220:221]
	global_load_dwordx4 v[192:195], v[220:221], off
	global_load_dwordx4 v[196:199], v[220:221], off offset:256
	v_add_u32_e32 v218, 0xa0, v164
	v_ashrrev_i32_e32 v219, 31, v218
	v_lshlrev_b64 v[220:221], 12, v[218:219]
	v_lshl_add_u64 v[220:221], v[166:167], 0, v[220:221]
	global_load_dwordx4 v[200:203], v[220:221], off
	global_load_dwordx4 v[204:207], v[220:221], off offset:256
	v_add_u32_e32 v218, 0xb0, v164
	v_ashrrev_i32_e32 v219, 31, v218
	v_lshlrev_b64 v[220:221], 12, v[218:219]
	v_lshl_add_u64 v[220:221], v[166:167], 0, v[220:221]
	global_load_dwordx4 v[210:213], v[220:221], off
	global_load_dwordx4 v[214:217], v[220:221], off offset:256
	s_cmp_eq_u32 s78, 3
	s_cselect_b64 s[0:1], -1, 0
	s_cmp_lg_u32 s78, 3
	v_lshlrev_b64 v[170:171], 11, v[164:165]
	s_cselect_b64 s[6:7], -1, 0
	v_or_b32_e32 v170, v170, v174
	s_mov_b64 s[2:3], -1
	s_and_b64 vcc, exec, s[6:7]
	v_lshl_add_u64 v[168:169], v[170:171], 1, s[44:45]
	s_mov_b64 s[8:9], 0x100
	s_waitcnt vmcnt(8)
	v_lshlrev_b32_e32 v180, 16, v176
	v_and_b32_e32 v181, 0xffff0000, v176
	v_lshlrev_b32_e32 v176, 16, v177
	v_and_b32_e32 v177, 0xffff0000, v177
	v_lshlrev_b32_e32 v182, 16, v178
	v_and_b32_e32 v183, 0xffff0000, v178
	v_lshlrev_b32_e32 v178, 16, v179
	v_and_b32_e32 v179, 0xffff0000, v179
	v_pk_add_f32 v[128:129], v[128:129], v[176:177]
	v_pk_add_f32 v[126:127], v[126:127], v[180:181]
	v_pk_add_f32 v[124:125], v[124:125], v[178:179]
	v_pk_add_f32 v[122:123], v[122:123], v[182:183]
	s_cbranch_vccz .LBB0_381
	v_cvt_pk_bf16_f32 v176, v126, v127
	v_cvt_pk_bf16_f32 v177, v128, v129
	v_cvt_pk_bf16_f32 v178, v122, v123
	v_cvt_pk_bf16_f32 v179, v124, v125
	s_mov_b64 s[2:3], 0
	global_store_dwordx4 v[168:169], v[176:179], off sc1
	s_nop 1
	v_pk_mul_f32 v[176:177], v[128:129], v[128:129]
	v_pk_mul_f32 v[178:179], v[126:127], v[126:127]
	s_nop 0
	v_pk_mov_b32 v[180:181], v[178:179], v[176:177] op_sel:[1,0]
	v_mov_b32_e32 v179, v177
	v_pk_add_f32 v[176:177], v[180:181], v[178:179]
	v_pk_mul_f32 v[178:179], v[124:125], v[124:125]
	v_pk_mul_f32 v[180:181], v[122:123], v[122:123]
	v_mov_b32_e32 v182, v178
	v_mov_b32_e32 v183, v180
	v_mov_b32_e32 v180, v179
	v_pk_add_f32 v[178:179], v[182:183], v[180:181]
	v_add_f32_e32 v0, v176, v177
	v_add_f32_e32 v0, v179, v0
	v_add_f32_e32 v175, v178, v0

.LBB0_411:
	v_add_u32_e32 v100, 0x80, v164
	v_ashrrev_i32_e32 v101, 31, v100
	v_lshlrev_b64 v[66:67], 12, v[100:101]
	v_add_u32_e32 v98, 0x90, v164
	v_lshl_add_u64 v[66:67], v[166:167], 0, v[66:67]
	v_ashrrev_i32_e32 v99, 31, v98
	s_waitcnt vmcnt(8)
	v_mov_b32_e32 v110, v184
	v_mov_b32_e32 v111, v185
	v_mov_b32_e32 v112, v186
	v_mov_b32_e32 v113, v187
	v_mov_b32_e32 v90, v188
	v_mov_b32_e32 v91, v189
	v_mov_b32_e32 v92, v190
	v_mov_b32_e32 v93, v191
	v_lshlrev_b64 v[66:67], 12, v[98:99]
	v_add_u32_e32 v96, 0xa0, v164
	v_lshl_add_u64 v[66:67], v[166:167], 0, v[66:67]
	v_ashrrev_i32_e32 v97, 31, v96
	v_mov_b32_e32 v86, v192
	v_mov_b32_e32 v87, v193
	v_mov_b32_e32 v88, v194
	v_mov_b32_e32 v89, v195
	v_mov_b32_e32 v82, v196
	v_mov_b32_e32 v83, v197
	v_mov_b32_e32 v84, v198
	v_mov_b32_e32 v85, v199
	v_lshlrev_b64 v[66:67], 12, v[96:97]
	v_add_u32_e32 v94, 0xb0, v164
	v_lshl_add_u64 v[66:67], v[166:167], 0, v[66:67]
	v_ashrrev_i32_e32 v95, 31, v94
	v_mov_b32_e32 v78, v200
	v_mov_b32_e32 v79, v201
	v_mov_b32_e32 v80, v202
	v_mov_b32_e32 v81, v203
	v_mov_b32_e32 v74, v204
	v_mov_b32_e32 v75, v205
	v_mov_b32_e32 v76, v206
	v_mov_b32_e32 v77, v207
	v_lshlrev_b64 v[66:67], 12, v[94:95]
	v_lshl_add_u64 v[66:67], v[166:167], 0, v[66:67]
	v_mov_b32_e32 v70, v210
	v_mov_b32_e32 v71, v211
	v_mov_b32_e32 v72, v212
	v_mov_b32_e32 v73, v213
	s_nop 0
	v_mov_b32_e32 v66, v214
	v_mov_b32_e32 v67, v215
	v_mov_b32_e32 v68, v216
	v_mov_b32_e32 v69, v217
	v_lshlrev_b64 v[104:105], 11, v[100:101]
	v_or_b32_e32 v104, v104, v174
	s_mov_b64 s[2:3], -1
	s_and_b64 vcc, exec, s[6:7]
	v_lshl_add_u64 v[102:103], v[104:105], 1, s[44:45]
	v_lshlrev_b32_e32 v114, 16, v110
	v_and_b32_e32 v115, 0xffff0000, v110
	v_lshlrev_b32_e32 v110, 16, v111
	v_and_b32_e32 v111, 0xffff0000, v111
	v_lshlrev_b32_e32 v116, 16, v112
	v_and_b32_e32 v117, 0xffff0000, v112
	v_lshlrev_b32_e32 v112, 16, v113
	v_and_b32_e32 v113, 0xffff0000, v113
	v_pk_add_f32 v[64:65], v[64:65], v[110:111]
	v_pk_add_f32 v[62:63], v[62:63], v[114:115]
	v_pk_add_f32 v[60:61], v[60:61], v[112:113]
	v_pk_add_f32 v[58:59], v[58:59], v[116:117]
	s_cbranch_vccz .LBB0_413
	v_cvt_pk_bf16_f32 v110, v62, v63
	v_cvt_pk_bf16_f32 v111, v64, v65
	v_cvt_pk_bf16_f32 v112, v58, v59
	v_cvt_pk_bf16_f32 v113, v60, v61
	s_mov_b64 s[2:3], 0
	global_store_dwordx4 v[102:103], v[110:113], off sc1
	s_nop 1
	v_pk_mul_f32 v[110:111], v[64:65], v[64:65]
	v_pk_mul_f32 v[112:113], v[62:63], v[62:63]
	s_nop 0
	v_pk_mov_b32 v[114:115], v[112:113], v[110:111] op_sel:[1,0]
	v_mov_b32_e32 v113, v111
	v_pk_add_f32 v[110:111], v[114:115], v[112:113]
	v_pk_mul_f32 v[112:113], v[60:61], v[60:61]
	v_pk_mul_f32 v[114:115], v[58:59], v[58:59]
	v_mov_b32_e32 v116, v112
	v_mov_b32_e32 v117, v114
	v_mov_b32_e32 v114, v113
	v_pk_add_f32 v[112:113], v[116:117], v[114:115]
	v_add_f32_e32 v109, v110, v111
	v_add_f32_e32 v109, v113, v109
	v_add_f32_e32 v109, v112, v109

.LBB0_415:
	s_nop 0
	v_lshlrev_b32_e32 v58, 16, v90
	v_and_b32_e32 v59, 0xffff0000, v90
	v_lshlrev_b32_e32 v60, 16, v91
	v_and_b32_e32 v61, 0xffff0000, v91
	v_pk_add_f32 v[56:57], v[56:57], v[60:61]
	v_pk_add_f32 v[54:55], v[54:55], v[58:59]
	v_lshlrev_b32_e32 v58, 16, v92
	v_and_b32_e32 v59, 0xffff0000, v92
	v_lshlrev_b32_e32 v60, 16, v93
	v_and_b32_e32 v61, 0xffff0000, v93
	v_pk_add_f32 v[52:53], v[52:53], v[60:61]
	v_pk_add_f32 v[50:51], v[50:51], v[58:59]
	s_mov_b64 s[2:3], -1
	s_and_b64 vcc, exec, s[6:7]
	s_cbranch_vccz .LBB0_417
	v_cvt_pk_bf16_f32 v58, v54, v55
	v_cvt_pk_bf16_f32 v59, v56, v57
	v_cvt_pk_bf16_f32 v60, v50, v51
	v_cvt_pk_bf16_f32 v61, v52, v53
	v_lshl_add_u64 v[62:63], v[102:103], 0, s[8:9]
	global_store_dwordx4 v[62:63], v[58:61], off sc1
	s_nop 1
	v_pk_mul_f32 v[58:59], v[56:57], v[56:57]
	v_pk_mul_f32 v[60:61], v[54:55], v[54:55]
	s_mov_b64 s[2:3], 0
	v_pk_mov_b32 v[62:63], v[60:61], v[58:59] op_sel:[1,0]
	v_mov_b32_e32 v61, v59
	v_pk_add_f32 v[58:59], v[62:63], v[60:61]
	v_pk_mul_f32 v[60:61], v[52:53], v[52:53]
	v_pk_mul_f32 v[62:63], v[50:51], v[50:51]
	v_mov_b32_e32 v64, v60
	v_mov_b32_e32 v65, v62
	v_mov_b32_e32 v62, v61
	v_pk_add_f32 v[60:61], v[64:65], v[62:63]
	v_add_f32_e32 v58, v58, v59
	v_add_f32_e32 v58, v61, v58
	v_add_f32_e32 v58, v60, v58
	v_add_f32_e32 v58, v58, v109

.LBB0_419:
	s_nop 1
	v_lshlrev_b64 v[52:53], 11, v[98:99]
	v_lshlrev_b32_e32 v50, 16, v86
	v_and_b32_e32 v51, 0xffff0000, v86
	v_lshlrev_b32_e32 v54, 16, v87
	v_and_b32_e32 v55, 0xffff0000, v87
	v_or_b32_e32 v52, v52, v174
	v_pk_add_f32 v[48:49], v[48:49], v[54:55]
	v_pk_add_f32 v[46:47], v[46:47], v[50:51]
	v_lshlrev_b32_e32 v50, 16, v88
	v_and_b32_e32 v51, 0xffff0000, v88
	v_lshlrev_b32_e32 v54, 16, v89
	v_and_b32_e32 v55, 0xffff0000, v89
	v_pk_add_f32 v[44:45], v[44:45], v[54:55]
	v_pk_add_f32 v[42:43], v[42:43], v[50:51]
	s_mov_b64 s[2:3], -1
	s_and_b64 vcc, exec, s[6:7]
	v_lshl_add_u64 v[50:51], v[52:53], 1, s[44:45]
	s_cbranch_vccz .LBB0_421
	v_cvt_pk_bf16_f32 v54, v46, v47
	v_cvt_pk_bf16_f32 v55, v48, v49
	v_cvt_pk_bf16_f32 v56, v42, v43
	v_cvt_pk_bf16_f32 v57, v44, v45
	s_mov_b64 s[2:3], 0
	global_store_dwordx4 v[50:51], v[54:57], off sc1
	s_nop 1
	v_pk_mul_f32 v[54:55], v[48:49], v[48:49]
	v_pk_mul_f32 v[56:57], v[46:47], v[46:47]
	s_nop 0
	v_pk_mov_b32 v[60:61], v[56:57], v[54:55] op_sel:[1,0]
	v_mov_b32_e32 v57, v55
	v_pk_add_f32 v[54:55], v[60:61], v[56:57]
	v_pk_mul_f32 v[56:57], v[44:45], v[44:45]
	v_pk_mul_f32 v[60:61], v[42:43], v[42:43]
	v_mov_b32_e32 v62, v56
	v_mov_b32_e32 v63, v60
	v_mov_b32_e32 v60, v57
	v_pk_add_f32 v[56:57], v[62:63], v[60:61]
	v_add_f32_e32 v54, v54, v55
	v_add_f32_e32 v54, v57, v54
	v_add_f32_e32 v54, v56, v54

.LBB0_423:
	s_nop 0
	v_lshlrev_b32_e32 v42, 16, v82
	v_and_b32_e32 v43, 0xffff0000, v82
	v_lshlrev_b32_e32 v44, 16, v83
	v_and_b32_e32 v45, 0xffff0000, v83
	v_pk_add_f32 v[40:41], v[40:41], v[44:45]
	v_pk_add_f32 v[38:39], v[38:39], v[42:43]
	v_lshlrev_b32_e32 v42, 16, v84
	v_and_b32_e32 v43, 0xffff0000, v84
	v_lshlrev_b32_e32 v44, 16, v85
	v_and_b32_e32 v45, 0xffff0000, v85
	v_pk_add_f32 v[36:37], v[36:37], v[44:45]
	v_pk_add_f32 v[34:35], v[34:35], v[42:43]
	s_mov_b64 s[2:3], -1
	s_and_b64 vcc, exec, s[6:7]
	s_cbranch_vccz .LBB0_425
	v_cvt_pk_bf16_f32 v42, v38, v39
	v_cvt_pk_bf16_f32 v43, v40, v41
	v_cvt_pk_bf16_f32 v44, v34, v35
	v_cvt_pk_bf16_f32 v45, v36, v37
	v_lshl_add_u64 v[46:47], v[50:51], 0, s[8:9]
	global_store_dwordx4 v[46:47], v[42:45], off sc1
	s_nop 1
	v_pk_mul_f32 v[42:43], v[40:41], v[40:41]
	v_pk_mul_f32 v[44:45], v[38:39], v[38:39]
	s_mov_b64 s[2:3], 0
	v_pk_mov_b32 v[46:47], v[44:45], v[42:43] op_sel:[1,0]
	v_mov_b32_e32 v45, v43
	v_pk_add_f32 v[42:43], v[46:47], v[44:45]
	v_pk_mul_f32 v[44:45], v[36:37], v[36:37]
	v_pk_mul_f32 v[46:47], v[34:35], v[34:35]
	v_mov_b32_e32 v48, v44
	v_mov_b32_e32 v49, v46
	v_mov_b32_e32 v46, v45
	v_pk_add_f32 v[44:45], v[48:49], v[46:47]
	v_add_f32_e32 v42, v42, v43
	v_add_f32_e32 v42, v45, v42
	v_add_f32_e32 v42, v44, v42
	v_add_f32_e32 v42, v42, v54

.LBB0_427:
	s_nop 1
	v_lshlrev_b64 v[36:37], 11, v[96:97]
	v_lshlrev_b32_e32 v34, 16, v78
	v_and_b32_e32 v35, 0xffff0000, v78
	v_lshlrev_b32_e32 v38, 16, v79
	v_and_b32_e32 v39, 0xffff0000, v79
	v_or_b32_e32 v36, v36, v174
	v_pk_add_f32 v[32:33], v[32:33], v[38:39]
	v_pk_add_f32 v[30:31], v[30:31], v[34:35]
	v_lshlrev_b32_e32 v34, 16, v80
	v_and_b32_e32 v35, 0xffff0000, v80
	v_lshlrev_b32_e32 v38, 16, v81
	v_and_b32_e32 v39, 0xffff0000, v81
	v_pk_add_f32 v[28:29], v[28:29], v[38:39]
	v_pk_add_f32 v[26:27], v[26:27], v[34:35]
	s_mov_b64 s[2:3], -1
	s_and_b64 vcc, exec, s[6:7]
	v_lshl_add_u64 v[34:35], v[36:37], 1, s[44:45]
	s_cbranch_vccz .LBB0_429
	v_cvt_pk_bf16_f32 v38, v30, v31
	v_cvt_pk_bf16_f32 v39, v32, v33
	v_cvt_pk_bf16_f32 v40, v26, v27
	v_cvt_pk_bf16_f32 v41, v28, v29
	s_mov_b64 s[2:3], 0
	global_store_dwordx4 v[34:35], v[38:41], off sc1
	s_nop 1
	v_pk_mul_f32 v[38:39], v[32:33], v[32:33]
	v_pk_mul_f32 v[40:41], v[30:31], v[30:31]
	s_nop 0
	v_pk_mov_b32 v[44:45], v[40:41], v[38:39] op_sel:[1,0]
	v_mov_b32_e32 v41, v39
	v_pk_add_f32 v[38:39], v[44:45], v[40:41]
	v_pk_mul_f32 v[40:41], v[28:29], v[28:29]
	v_pk_mul_f32 v[44:45], v[26:27], v[26:27]
	v_mov_b32_e32 v46, v40
	v_mov_b32_e32 v47, v44
	v_mov_b32_e32 v44, v41
	v_pk_add_f32 v[40:41], v[46:47], v[44:45]
	v_add_f32_e32 v38, v38, v39
	v_add_f32_e32 v38, v41, v38
	v_add_f32_e32 v38, v40, v38

.LBB0_431:
	s_nop 0
	v_lshlrev_b32_e32 v26, 16, v74
	v_and_b32_e32 v27, 0xffff0000, v74
	v_lshlrev_b32_e32 v28, 16, v75
	v_and_b32_e32 v29, 0xffff0000, v75
	v_pk_add_f32 v[24:25], v[24:25], v[28:29]
	v_pk_add_f32 v[22:23], v[22:23], v[26:27]
	v_lshlrev_b32_e32 v26, 16, v76
	v_and_b32_e32 v27, 0xffff0000, v76
	v_lshlrev_b32_e32 v28, 16, v77
	v_and_b32_e32 v29, 0xffff0000, v77
	v_pk_add_f32 v[20:21], v[20:21], v[28:29]
	v_pk_add_f32 v[18:19], v[18:19], v[26:27]
	s_mov_b64 s[2:3], -1
	s_and_b64 vcc, exec, s[6:7]
	s_cbranch_vccz .LBB0_433
	v_cvt_pk_bf16_f32 v26, v22, v23
	v_cvt_pk_bf16_f32 v27, v24, v25
	v_cvt_pk_bf16_f32 v28, v18, v19
	v_cvt_pk_bf16_f32 v29, v20, v21
	v_lshl_add_u64 v[30:31], v[34:35], 0, s[8:9]
	global_store_dwordx4 v[30:31], v[26:29], off sc1
	s_nop 1
	v_pk_mul_f32 v[26:27], v[24:25], v[24:25]
	v_pk_mul_f32 v[28:29], v[22:23], v[22:23]
	s_mov_b64 s[2:3], 0
	v_pk_mov_b32 v[30:31], v[28:29], v[26:27] op_sel:[1,0]
	v_mov_b32_e32 v29, v27
	v_pk_add_f32 v[26:27], v[30:31], v[28:29]
	v_pk_mul_f32 v[28:29], v[20:21], v[20:21]
	v_pk_mul_f32 v[30:31], v[18:19], v[18:19]
	v_mov_b32_e32 v32, v28
	v_mov_b32_e32 v33, v30
	v_mov_b32_e32 v30, v29
	v_pk_add_f32 v[28:29], v[32:33], v[30:31]
	v_add_f32_e32 v26, v26, v27
	v_add_f32_e32 v26, v29, v26
	v_add_f32_e32 v26, v28, v26
	v_add_f32_e32 v26, v26, v38

.LBB0_435:
	s_nop 1
	v_lshlrev_b64 v[20:21], 11, v[94:95]
	v_lshlrev_b32_e32 v18, 16, v70
	v_and_b32_e32 v19, 0xffff0000, v70
	v_lshlrev_b32_e32 v22, 16, v71
	v_and_b32_e32 v23, 0xffff0000, v71
	v_or_b32_e32 v20, v20, v174
	v_pk_add_f32 v[16:17], v[16:17], v[22:23]
	v_pk_add_f32 v[14:15], v[14:15], v[18:19]
	v_lshlrev_b32_e32 v18, 16, v72
	v_and_b32_e32 v19, 0xffff0000, v72
	v_lshlrev_b32_e32 v22, 16, v73
	v_and_b32_e32 v23, 0xffff0000, v73
	v_pk_add_f32 v[12:13], v[12:13], v[22:23]
	v_pk_add_f32 v[10:11], v[10:11], v[18:19]
	s_mov_b64 s[2:3], -1
	s_and_b64 vcc, exec, s[6:7]
	v_lshl_add_u64 v[18:19], v[20:21], 1, s[44:45]
	s_cbranch_vccz .LBB0_437
	v_cvt_pk_bf16_f32 v22, v14, v15
	v_cvt_pk_bf16_f32 v23, v16, v17
	v_cvt_pk_bf16_f32 v24, v10, v11
	v_cvt_pk_bf16_f32 v25, v12, v13
	s_mov_b64 s[2:3], 0
	global_store_dwordx4 v[18:19], v[22:25], off sc1
	s_nop 1
	v_pk_mul_f32 v[22:23], v[16:17], v[16:17]
	v_pk_mul_f32 v[24:25], v[14:15], v[14:15]
	s_nop 0
	v_pk_mov_b32 v[28:29], v[24:25], v[22:23] op_sel:[1,0]
	v_mov_b32_e32 v25, v23
	v_pk_add_f32 v[22:23], v[28:29], v[24:25]
	v_pk_mul_f32 v[24:25], v[12:13], v[12:13]
	v_pk_mul_f32 v[28:29], v[10:11], v[10:11]
	v_mov_b32_e32 v30, v24
	v_mov_b32_e32 v31, v28
	v_mov_b32_e32 v28, v25
	v_pk_add_f32 v[24:25], v[30:31], v[28:29]
	v_add_f32_e32 v22, v22, v23
	v_add_f32_e32 v22, v25, v22
	v_add_f32_e32 v22, v24, v22

.LBB0_439:
	s_nop 0
	v_lshlrev_b32_e32 v10, 16, v66
	v_and_b32_e32 v11, 0xffff0000, v66
	v_lshlrev_b32_e32 v12, 16, v67
	v_and_b32_e32 v13, 0xffff0000, v67
	v_pk_add_f32 v[8:9], v[8:9], v[12:13]
	v_pk_add_f32 v[6:7], v[6:7], v[10:11]
	v_lshlrev_b32_e32 v10, 16, v68
	v_and_b32_e32 v11, 0xffff0000, v68
	v_lshlrev_b32_e32 v12, 16, v69
	v_and_b32_e32 v13, 0xffff0000, v69
	v_pk_add_f32 v[4:5], v[4:5], v[12:13]
	v_pk_add_f32 v[2:3], v[2:3], v[10:11]
	s_mov_b64 s[2:3], -1
	s_and_b64 vcc, exec, s[6:7]
	s_cbranch_vccz .LBB0_441
	v_cvt_pk_bf16_f32 v10, v6, v7
	v_cvt_pk_bf16_f32 v11, v8, v9
	v_cvt_pk_bf16_f32 v12, v2, v3
	v_cvt_pk_bf16_f32 v13, v4, v5
	v_lshl_add_u64 v[14:15], v[18:19], 0, s[8:9]
	global_store_dwordx4 v[14:15], v[10:13], off sc1
	s_nop 1
	v_pk_mul_f32 v[10:11], v[8:9], v[8:9]
	v_pk_mul_f32 v[12:13], v[6:7], v[6:7]
	s_mov_b64 s[2:3], 0
	v_pk_mov_b32 v[14:15], v[12:13], v[10:11] op_sel:[1,0]
	v_mov_b32_e32 v13, v11
	v_pk_add_f32 v[10:11], v[14:15], v[12:13]
	v_pk_mul_f32 v[12:13], v[4:5], v[4:5]
	v_pk_mul_f32 v[14:15], v[2:3], v[2:3]
	v_mov_b32_e32 v16, v12
	v_mov_b32_e32 v17, v14
	v_mov_b32_e32 v14, v13
	v_pk_add_f32 v[12:13], v[16:17], v[14:15]
	v_add_f32_e32 v10, v10, v11
	v_add_f32_e32 v10, v13, v10
	v_add_f32_e32 v10, v12, v10
	v_add_f32_e32 v10, v10, v22
